# pb4: chunk-scan waves run at s_setprio 3 (they are the phase's critical path beside 7 side waves per CU)
# baseline (speedup 1.0000x reference)
.LBB0_1315:
	s_and_b64 vcc, exec, s[0:1]
	s_cbranch_vccz .LBB0_1437
	s_setprio 3
	s_cmp_gt_i32 s87, 63
	s_mov_b64 s[0:1], -1
	s_cbranch_scc0 .LBB0_1413
	v_readlane_b32 s0, v255, 40
	v_readlane_b32 s1, v255, 41
	s_lshl_b32 s22, s0, 4
	s_add_i32 s0, s87, 0xffc0
	s_and_b32 s1, s0, 0xff
	s_mulk_i32 s1, 0xab
	s_bfe_u32 s1, s1, 0x3000d
	s_mul_i32 s2, s1, 48
	s_sub_i32 s0, s0, s2
	s_lshl_b32 s0, s0, 2
	s_bfe_i32 s2, s0, 0x80000
	s_or_b32 s0, s0, s1
	s_and_b32 s8, s0, 0xff
	s_sext_i32_i16 s0, s2
	s_cmp_lt_i32 s0, 0
	s_mov_b64 s[0:1], -1
	s_cbranch_scc0 .LBB0_1353
	s_add_i32 s0, s8, 0xffffff80
	s_lshr_b32 s6, s0, 4
	s_bfe_u32 s38, s8, 0x20002
	s_lshl_b32 s0, s6, 2
	s_or_b32 s15, s38, s0
	s_or_b32 s0, s15, 32
	s_and_b32 s14, s8, 3
	s_mul_hi_u32 s1, s0, 0xc3000
	s_mul_i32 s0, s0, 0xc3000
	s_add_u32 s9, s12, s0
	s_addc_u32 s16, s13, s1
	s_add_u32 s0, s9, 0x2e892000
	s_addc_u32 s1, s16, 0
	s_lshl_b32 s2, s6, 3
	s_or_b32 s2, s2, s38
	s_mul_hi_u32 s3, s2, 0x104
	s_mulk_i32 s2, 0x104
	s_or_b32 s2, s2, s14
	s_lshl_b64 s[2:3], s[2:3], 11
	s_add_u32 s17, s12, s2
	s_addc_u32 s18, s13, s3
	s_add_u32 s4, s17, 0x30f2a000
	s_addc_u32 s5, s18, 0
	s_mul_i32 s2, s6, 0x204000
	s_add_u32 s2, s12, s2
	s_addc_u32 s3, s13, 0
	s_lshl_b32 s7, s38, 8
	s_add_u32 s2, s2, s7
	s_addc_u32 s3, s3, 0
	s_lshl_b32 s7, s14, 5
	s_lshl_b32 s19, s14, 6
	s_add_u32 s2, s2, s19
	s_addc_u32 s3, s3, 0
	s_add_u32 s2, s2, 0x2c652000
	s_addc_u32 s3, s3, 0
	v_lshlrev_b32_e32 v110, 4, v224
	v_ashrrev_i32_e32 v111, 31, v110
	s_add_u32 s20, s9, 0x2e893000
	v_lshl_add_u64 v[4:5], s[0:1], 0, v[110:111]
	v_add_u32_e32 v112, 0x400, v110
	s_addc_u32 s21, s16, 0
	global_load_dwordx4 v[0:3], v[4:5], off
	global_load_dwordx4 v[16:19], v[4:5], off offset:1024
	v_ashrrev_i32_e32 v113, 31, v112
	v_add_u32_e32 v114, 0x800, v110
	global_load_dwordx4 v[20:23], v[4:5], off offset:2048
	global_load_dwordx4 v[24:27], v[4:5], off offset:3072
	v_lshl_add_u64 v[4:5], s[20:21], 0, v[110:111]
	v_ashrrev_i32_e32 v115, 31, v114
	v_add_u32_e32 v116, 0xc00, v110
	global_load_dwordx4 v[102:105], v[4:5], off
	v_lshl_add_u64 v[4:5], s[20:21], 0, v[112:113]
	v_ashrrev_i32_e32 v117, 31, v116
	global_load_dwordx4 v[44:47], v[4:5], off
	v_lshl_add_u64 v[4:5], s[20:21], 0, v[114:115]
	global_load_dwordx4 v[36:39], v[4:5], off
	v_lshl_add_u64 v[4:5], s[20:21], 0, v[116:117]
	s_add_u32 s20, s9, 0x2e894000
	s_addc_u32 s21, s16, 0
	global_load_dwordx4 v[32:35], v[4:5], off
	v_lshl_add_u64 v[4:5], s[4:5], 0, v[110:111]
	v_lshl_add_u64 v[6:7], s[20:21], 0, v[110:111]
	v_lshlrev_b32_e32 v118, 2, v224
	global_load_dwordx4 v[52:55], v[4:5], off
	global_load_dwordx4 v[28:31], v[6:7], off
	global_load_dwordx4 v[40:43], v[4:5], off offset:1024
	v_lshl_add_u64 v[4:5], s[20:21], 0, v[112:113]
	v_ashrrev_i32_e32 v119, 31, v118
	global_load_dwordx4 v[106:109], v[4:5], off
	v_lshl_add_u64 v[4:5], s[0:1], 0, v[118:119]
	v_add_co_u32_e32 v6, vcc, s74, v4
	s_add_u32 s20, s9, 0x2e895000
	s_nop 0
	v_addc_co_u32_e32 v7, vcc, 0, v5, vcc
	global_load_dword v8, v[6:7], off offset:2048
	s_addc_u32 s21, s16, 0
	v_lshl_add_u64 v[6:7], s[20:21], 0, v[110:111]
	s_waitcnt vmcnt(0)
	global_load_dwordx4 v[48:51], v[6:7], off
	v_lshl_add_u64 v[6:7], s[20:21], 0, v[112:113]
	global_load_dwordx4 v[80:83], v[6:7], off
	v_lshl_add_u64 v[6:7], s[20:21], 0, v[114:115]
	global_load_dwordx4 v[76:79], v[6:7], off
	v_lshl_add_u64 v[6:7], s[20:21], 0, v[116:117]
	s_add_u32 s20, s9, 0x2e896000
	s_addc_u32 s21, s16, 0
	global_load_dwordx4 v[72:75], v[6:7], off
	v_lshl_add_u64 v[6:7], s[20:21], 0, v[110:111]
	global_load_dwordx4 v[64:67], v[6:7], off
	v_lshl_add_u64 v[6:7], s[20:21], 0, v[112:113]
	global_load_dwordx4 v[92:95], v[6:7], off
	v_lshl_add_u64 v[6:7], s[20:21], 0, v[114:115]
	global_load_dwordx4 v[60:63], v[6:7], off
	v_lshl_add_u64 v[6:7], s[20:21], 0, v[116:117]
	s_add_u32 s20, s17, 0x30f2c000
	s_addc_u32 s21, s18, 0
	s_add_u32 s18, s9, 0x2e897000
	s_movk_i32 s9, 0x5000
	v_add_co_u32_e32 v4, vcc, s9, v4
	global_load_dwordx4 v[56:59], v[6:7], off
	s_nop 0
	v_addc_co_u32_e32 v5, vcc, 0, v5, vcc
	s_addc_u32 s19, s16, 0
	global_load_dword v157, v[4:5], off offset:2048
	v_lshl_add_u64 v[6:7], s[20:21], 0, v[110:111]
	global_load_dwordx4 v[68:71], v[6:7], off
	v_lshl_add_u64 v[6:7], s[18:19], 0, v[110:111]
	global_load_dwordx4 v[88:91], v[6:7], off
	v_lshl_add_u64 v[6:7], s[20:21], 0, v[112:113]
	global_load_dwordx4 v[98:101], v[6:7], off
	v_lshl_add_u64 v[6:7], s[18:19], 0, v[112:113]
	s_mov_b32 s18, s39
	s_mov_b32 s19, s39
	s_mov_b32 s16, s39
	s_mov_b32 s17, s39
	v_mov_b64_e32 v[122:123], s[18:19]
	v_add_u32_e32 v176, s86, v118
	v_mov_b64_e32 v[120:121], s[16:17]
	global_load_dwordx4 v[84:87], v[6:7], off
	v_and_b32_e32 v96, 31, v224
	v_lshlrev_b32_e32 v96, 1, v96
	v_lshl_add_u64 v[154:155], s[2:3], 0, v[96:97]
	s_add_i32 s15, s15, 32
	s_mov_b32 s9, 1
	s_mov_b32 s18, 0x2e89c000
	s_mov_b32 s19, 0x2e89d000
	s_mov_b64 s[20:21], 0x4000
	s_mov_b64 s[24:25], 0x6000
	ds_write_b32 v176, v8
	v_mfma_f32_32x32x16_bf16 v[0:15], v[0:3], v[120:123], 0
	v_mfma_f32_32x32x16_bf16 v[0:15], v[16:19], v[120:123], v[0:15]
	v_ashrrev_i32_e32 v18, 3, v224
	v_mfma_f32_32x32x16_bf16 v[0:15], v[20:23], v[120:123], v[0:15]
	v_mfma_f32_32x32x16_bf16 v[0:15], v[24:27], v[120:123], v[0:15]
	v_mfma_f32_32x32x16_bf16 v[0:15], v[28:31], v[52:55], v[0:15]
	v_mfma_f32_32x32x16_bf16 v[0:15], v[106:109], v[40:43], v[0:15]
	v_and_b32_e32 v106, -4, v18
	v_ashrrev_i32_e32 v107, 31, v106
	v_lshlrev_b64 v[16:17], 10, v[106:107]
	v_lshl_add_u64 v[16:17], v[154:155], 0, v[16:17]
	v_lshl_add_u32 v96, v106, 2, s86
	v_add_u32_e32 v156, 48, v106
	s_nop 5
	v_cvt_pk_bf16_f32 v0, v0, s0
	global_store_short v[16:17], v0, off
	v_or_b32_e32 v0, 1, v106
	v_cvt_pk_bf16_f32 v19, v1, s0
	v_ashrrev_i32_e32 v1, 31, v0
	v_lshlrev_b64 v[0:1], 10, v[0:1]
	v_lshl_add_u64 v[0:1], v[154:155], 0, v[0:1]
	global_store_short v[0:1], v19, off
	v_or_b32_e32 v0, 2, v106
	v_ashrrev_i32_e32 v1, 31, v0
	v_lshlrev_b64 v[0:1], 10, v[0:1]
	v_cvt_pk_bf16_f32 v2, v2, s0
	v_lshl_add_u64 v[0:1], v[154:155], 0, v[0:1]
	global_store_short v[0:1], v2, off
	v_or_b32_e32 v0, 3, v18
	v_ashrrev_i32_e32 v1, 31, v0
	v_lshlrev_b64 v[0:1], 10, v[0:1]
	v_cvt_pk_bf16_f32 v2, v3, s0
	v_lshl_add_u64 v[0:1], v[154:155], 0, v[0:1]
	global_store_short v[0:1], v2, off
	v_add_co_u32_e32 v2, vcc, s74, v16
	v_cvt_pk_bf16_f32 v4, v4, s0
	s_nop 0
	v_addc_co_u32_e32 v3, vcc, 0, v17, vcc
	global_store_short v[2:3], v4, off
	v_cvt_pk_bf16_f32 v4, v5, s0
	global_store_short v[2:3], v4, off offset:1024
	v_cvt_pk_bf16_f32 v4, v6, s0
	global_store_short v[2:3], v4, off offset:2048
	v_add_co_u32_e32 v2, vcc, s74, v0
	v_cvt_pk_bf16_f32 v4, v7, s0
	s_nop 0
	v_addc_co_u32_e32 v3, vcc, 0, v1, vcc
	global_store_short v[2:3], v4, off
	v_add_co_u32_e32 v2, vcc, s52, v16
	v_cvt_pk_bf16_f32 v4, v8, s0
	s_nop 0
	v_addc_co_u32_e32 v3, vcc, 0, v17, vcc
	global_store_short v[2:3], v4, off
	v_cvt_pk_bf16_f32 v4, v9, s0
	global_store_short v[2:3], v4, off offset:1024
	v_cvt_pk_bf16_f32 v4, v10, s0
	global_store_short v[2:3], v4, off offset:2048
	v_add_co_u32_e32 v2, vcc, s52, v0
	v_cvt_pk_bf16_f32 v4, v11, s0
	s_nop 0
	v_addc_co_u32_e32 v3, vcc, 0, v1, vcc
	global_store_short v[2:3], v4, off
	v_add_co_u32_e32 v2, vcc, s53, v16
	v_cvt_pk_bf16_f32 v4, v12, s0
	s_nop 0
	v_addc_co_u32_e32 v3, vcc, 0, v17, vcc
	global_store_short v[2:3], v4, off
	v_cvt_pk_bf16_f32 v4, v13, s0
	global_store_short v[2:3], v4, off offset:1024
	v_cvt_pk_bf16_f32 v4, v14, s0
	v_add_co_u32_e32 v0, vcc, s53, v0
	global_store_short v[2:3], v4, off offset:2048
	v_cvt_pk_bf16_f32 v2, v15, s0
	v_addc_co_u32_e32 v1, vcc, 0, v1, vcc
	global_store_short v[0:1], v2, off
	ds_read_b128 v[0:3], v96 offset:128
	ds_read_b128 v[4:7], v96
	ds_read_b128 v[8:11], v96 offset:32
	ds_read_b128 v[120:123], v96 offset:160
	ds_read_b128 v[12:15], v96 offset:64
	ds_read_b128 v[124:127], v96 offset:192
	ds_read_b128 v[16:19], v96 offset:96
	ds_read_b128 v[128:131], v96 offset:224
	s_waitcnt lgkmcnt(5)
	v_pk_mul_f32 v[22:23], v[10:11], 0 op_sel_hi:[1,0]
	s_waitcnt lgkmcnt(3)
	v_pk_mul_f32 v[26:27], v[14:15], 0 op_sel_hi:[1,0]
	v_pk_mul_f32 v[24:25], v[12:13], 0 op_sel_hi:[1,0]
	s_waitcnt lgkmcnt(1)
	v_pk_mul_f32 v[30:31], v[18:19], 0 op_sel_hi:[1,0]
	v_pk_mul_f32 v[18:19], v[6:7], 0 op_sel_hi:[1,0]
	v_pk_mul_f32 v[28:29], v[16:17], 0 op_sel_hi:[1,0]
	v_pk_mul_f32 v[20:21], v[8:9], 0 op_sel_hi:[1,0]
	v_pk_mul_f32 v[16:17], v[4:5], 0 op_sel_hi:[1,0]
	s_waitcnt lgkmcnt(0)
	v_pk_mul_f32 v[14:15], v[130:131], 0 op_sel_hi:[1,0]
	v_pk_mul_f32 v[10:11], v[126:127], 0 op_sel_hi:[1,0]
	v_pk_mul_f32 v[6:7], v[122:123], 0 op_sel_hi:[1,0]
	v_pk_mul_f32 v[2:3], v[2:3], 0 op_sel_hi:[1,0]
	v_pk_mul_f32 v[12:13], v[128:129], 0 op_sel_hi:[1,0]
	v_pk_mul_f32 v[8:9], v[124:125], 0 op_sel_hi:[1,0]
	v_pk_mul_f32 v[4:5], v[120:121], 0 op_sel_hi:[1,0]
	v_pk_mul_f32 v[0:1], v[0:1], 0 op_sel_hi:[1,0]
	v_mfma_f32_32x32x16_bf16 v[16:31], v[102:105], v[52:55], v[16:31]
	s_nop 0
	v_mfma_f32_32x32x16_bf16 v[0:15], v[36:39], v[52:55], v[0:15]
	v_mfma_f32_32x32x16_bf16 v[16:31], v[44:47], v[40:43], v[16:31]
	v_mfma_f32_32x32x16_bf16 v[0:15], v[32:35], v[40:43], v[0:15]
	v_mov_b32_e32 v32, 0xc3000
	v_mad_u64_u32 v[158:159], s[16:17], s15, v32, v[110:111]
	v_mad_u64_u32 v[160:161], s[16:17], s15, v32, v[112:113]
	v_mad_u64_u32 v[162:163], s[16:17], s15, v32, v[114:115]
	v_mad_u64_u32 v[164:165], s[16:17], s15, v32, v[116:117]
	v_mad_u64_u32 v[166:167], s[16:17], s15, v32, v[118:119]
	s_mul_i32 s16, s6, 0x410000
	s_mul_i32 s17, s38, 0x82000
	s_mul_hi_u32 s15, s6, 0x410000
	s_add_u32 s16, s16, s17
	s_addc_u32 s15, s15, 0
	s_lshl_b32 s14, s14, 11
	s_or_b32 s14, s16, s14
	v_lshl_add_u64 v[168:169], s[14:15], 0, v[110:111]
	s_mov_b32 s15, 0x2e898000
	s_mov_b32 s16, 0x2e89a000
	s_mov_b32 s17, 0x2e89b000

.LBB0_1437:
	s_setprio 0
	v_readlane_b32 s54, v253, 30
	v_readlane_b32 s69, v255, 4
	v_readlane_b32 s28, v253, 32
	v_readlane_b32 s55, v253, 31
	s_mov_b32 s0, s69
	s_waitcnt vmcnt(0)
	s_cmp_eq_u32 s0, 0
	v_readlane_b32 s68, v255, 5
	s_waitcnt vmcnt(63) expcnt(7) lgkmcnt(15)
	s_barrier
	s_cbranch_scc0 .LBB0_1511
	s_mov_b32 s0, -1
	s_nop 0
	v_mbcnt_lo_u32_b32 v0, s0, 0
	v_mbcnt_hi_u32_b32 v0, s0, v0
	v_cmp_eq_u32_e32 vcc, 0, v0
	s_and_saveexec_b64 s[56:57], vcc
	s_cbranch_execz .LBB0_1510
	v_readlane_b32 s0, v254, 40
	s_waitcnt vmcnt(0) expcnt(0) lgkmcnt(0)
	s_nop 0
	v_mov_b32_e32 v0, s0
	ds_read_b32 v2, v0
	v_readlane_b32 s0, v254, 41
	s_waitcnt lgkmcnt(0)
	v_cmp_ne_u32_e32 vcc, 0, v2
	v_mov_b32_e32 v0, s0
	ds_read_b32 v0, v0
	s_cbranch_vccnz .LBB0_1481
	v_readlane_b32 s0, v253, 0
	v_readlane_b32 s1, v253, 1
	s_load_dwordx2 s[4:5], s[0:1], 0x4
	s_add_u32 s0, s54, 0x1000
	s_addc_u32 s1, s55, 0
	s_add_u32 s2, s54, 0x1100
	s_addc_u32 s3, s55, 0
	s_waitcnt lgkmcnt(0)
	s_mul_i32 s26, s4, s68
	s_add_u32 s4, s54, 0x1200
	s_mul_i32 s26, s26, s5
	s_addc_u32 s5, s55, 0
	s_add_u32 s6, s54, 0x1300
	s_addc_u32 s7, s55, 0
	s_mov_b32 s27, 1
	s_mov_b64 s[8:9], 0
	s_branch .LBB0_1443
